# speedup vs baseline: 1.0111x; 1.0111x over previous
.LBB0_349:
	s_mov_b64 s[2:3], s[76:77]
	v_readlane_b32 s4, v254, 39
	v_mbcnt_lo_u32_b32 v2, -1, 0
	v_mbcnt_hi_u32_b32 v2, -1, v2
	s_nop 0
	v_and_b32_e32 v3, 48, v2
	v_add_u32_e32 v1, s4, v2
	v_lshlrev_b32_e32 v4, 6, v1
	v_readfirstlane_b32 s14, v1
	s_ashr_i32 s8, s14, 6
	s_ashr_i32 s12, s14, 8
	s_and_b32 s13, s8, 3
	s_lshl_b32 s4, s12, 13
	v_lshlrev_b32_e32 v5, 2, v1
	s_cmp_lg_u32 0, -1
	v_and_b32_e32 v4, 0x3c0, v4
	v_and_b32_e32 v5, 32, v5
	s_cselect_b32 s5, 0, 0
	v_bitop3_b32 v3, v4, v5, v3 bitop3:0x36
	s_add_i32 s4, s4, s5
	v_add_u32_e32 v136, s4, v3
	s_lshl_b32 s4, s13, 12
	s_add_i32 s4, s5, s4
	s_add_i32 s4, s4, 0x10000
	v_add_u32_e32 v137, s4, v3
	v_readlane_b32 s4, v254, 11
	v_readlane_b32 s5, v254, 12
	s_andn2_b64 vcc, exec, s[4:5]
	s_cbranch_vccnz .LBB0_370
	s_waitcnt lgkmcnt(0)
	s_load_dwordx2 s[10:11], s[2:3], 0xe8
	v_cmp_gt_i32_e64 s[4:5], s0, v1
	v_mov_b32_e32 v206, 0
	s_waitcnt lgkmcnt(0)
	s_add_u32 s2, s10, 0x1b300000
	s_addc_u32 s3, s11, 0
	s_and_saveexec_b64 s[6:7], s[4:5]
	s_cbranch_execz .LBB0_352
	v_readlane_b32 s16, v254, 19
	v_readlane_b32 s17, v254, 20
	s_nop 0
	v_add_u32_e32 v4, s16, v1
	v_ashrrev_i32_e32 v5, 31, v4
	v_lshl_add_u64 v[4:5], v[4:5], 4, s[2:3]
	global_load_dwordx4 v[160:163], v[4:5], off
.LBB0_352:
	s_or_b64 exec, exec, s[6:7]
	v_bfe_i32 v5, v1, 27, 1
	v_lshlrev_b32_e32 v3, 4, v1
	v_lshrrev_b32_e32 v5, 22, v5
	v_add_u32_e32 v5, v3, v5
	v_and_b32_e32 v5, 0xfffffc00, v5
	v_sub_u32_e32 v5, v3, v5
	v_lshrrev_b32_e32 v6, 4, v5
	v_ashrrev_i32_e32 v4, 31, v1
	v_bitop3_b32 v5, v6, v5, 32 bitop3:0x6c
	v_lshrrev_b32_e32 v4, 26, v4
	v_ashrrev_i32_e32 v7, 31, v5
	v_add_u32_e32 v4, v1, v4
	v_lshrrev_b32_e32 v7, 26, v7
	v_ashrrev_i32_e32 v4, 6, v4
	v_add_u32_e32 v7, v5, v7
	v_lshlrev_b32_e32 v6, 3, v4
	v_lshrrev_b32_e32 v8, 6, v7
	v_and_b32_e32 v7, 0xc0, v7
	v_and_b32_e32 v6, 0x1ffff0, v6
	v_lshlrev_b32_e32 v4, 5, v4
	v_sub_u32_e32 v5, v5, v7
	v_add_u32_e32 v6, v8, v6
	v_and_b32_e32 v4, 32, v4
	v_ashrrev_i16_sdwa v5, v207, sext(v5) dst_sel:DWORD dst_unused:UNUSED_PAD src0_sel:DWORD src1_sel:BYTE_0
	v_bfe_i32 v5, v5, 0, 16
	v_lshl_or_b32 v4, v6, 10, v4
	v_add_u32_e32 v3, 0x2000, v3
	v_add_lshl_u32 v130, v4, v5, 1
	v_ashrrev_i32_e32 v4, 31, v3
	s_add_u32 s22, s10, 0x5300000
	v_lshrrev_b32_e32 v4, 22, v4
	s_addc_u32 s23, s11, 0
	v_add_u32_e32 v4, v3, v4
	s_cmp_eq_u32 s99, 3
	s_mov_b32 s6, 0x4200000
	v_ashrrev_i32_e32 v4, 10, v4
	s_cselect_b32 s6, s6, 0x4a08000
	v_mul_i32_i24_e32 v5, 0x400, v4
	s_add_u32 s24, s10, s6
	v_sub_u32_e32 v3, v3, v5
	s_addc_u32 s25, s11, 0
	v_lshrrev_b32_e32 v5, 4, v3
	s_add_u32 s6, s10, 0x9300000
	v_bitop3_b32 v3, v5, v3, 32 bitop3:0x6c
	s_mul_i32 s9, s8, 0x900
	s_addc_u32 s7, s11, 0
	v_ashrrev_i32_e32 v6, 31, v3
	s_add_i32 s26, s9, 0
	v_lshrrev_b32_e32 v6, 26, v6
	s_add_i32 s26, s26, 0x20000
	v_readlane_b32 s16, v254, 13
	v_add_u32_e32 v6, v3, v6
	v_readlane_b32 s17, v254, 14
	s_add_u32 s16, s24, s16
	v_lshlrev_b32_e32 v5, 3, v4
	v_lshrrev_b32_e32 v7, 6, v6
	v_and_b32_e32 v6, 0xc0, v6
	s_addc_u32 s17, s25, s17
	s_lshl_b32 s8, s8, 10
	v_and_b32_e32 v5, 0x1ffff0, v5
	v_lshlrev_b32_e32 v4, 5, v4
	v_sub_u32_e32 v3, v3, v6
	s_add_i32 s27, s8, 0
	v_add_u32_e32 v5, v7, v5
	v_and_b32_e32 v4, 32, v4
	v_ashrrev_i16_sdwa v3, v207, sext(v3) dst_sel:DWORD dst_unused:UNUSED_PAD src0_sel:DWORD src1_sel:BYTE_0
	s_add_i32 s28, s27, 0x10000
	s_add_i32 s29, s27, 0x12000
	v_readlane_b32 s8, v254, 15
	v_bfe_i32 v3, v3, 0, 16
	v_lshl_or_b32 v4, v5, 10, v4
	s_mov_b64 s[18:19], s[16:17]
	s_mov_b32 m0, s28
	v_readlane_b32 s9, v254, 16
	s_add_u32 s8, s22, s8
	v_add_lshl_u32 v132, v4, v3, 1
	s_addc_u32 s9, s23, s9
	global_load_lds_dwordx4 v130, s[18:19]
	s_mov_b32 m0, s29
	s_add_i32 s30, s27, 0x2000
	global_load_lds_dwordx4 v132, s[18:19]
	s_mov_b64 s[18:19], s[8:9]
	s_mov_b32 m0, s27
	v_readlane_b32 s15, v254, 44
	global_load_lds_dwordx4 v130, s[18:19]
	s_mov_b32 m0, s30
	v_and_b32_e32 v252, 63, v2
	global_load_lds_dwordx4 v132, s[18:19]
	v_readlane_b32 s18, v254, 17
	v_readlane_b32 s19, v254, 18
	s_add_u32 s18, s24, s18
	s_addc_u32 s19, s25, s19
	s_add_i32 s31, s27, 0x14000
	s_mov_b64 s[20:21], s[18:19]
	s_mov_b32 m0, s31
	s_add_i32 s33, s27, 0x16000
	v_mov_b32_e32 v131, v0
	global_load_lds_dwordx4 v130, s[20:21]
	s_mov_b32 m0, s33
	v_mov_b32_e32 v133, v0
	global_load_lds_dwordx4 v132, s[20:21]
	v_readlane_b32 s20, v254, 21
	v_readlane_b32 s21, v254, 22
	s_add_u32 s20, s22, s20
	s_addc_u32 s21, s23, s21
	s_add_i32 s34, s27, 0x4000
	s_mov_b64 s[36:37], s[20:21]
	s_mov_b32 m0, s34
	s_add_i32 s35, s27, 0x6000
	s_add_u32 s16, s16, 0x80
	global_load_lds_dwordx4 v130, s[36:37]
	s_mov_b32 m0, s35
	s_addc_u32 s17, s17, 0
	global_load_lds_dwordx4 v132, s[36:37]
	s_add_i32 s36, s27, 0x18000
	s_add_i32 s37, s27, 0x1a000
	s_mov_b32 m0, s36
	s_add_u32 s8, s8, 0x80
	s_addc_u32 s9, s9, 0
	global_load_lds_dwordx4 v130, s[16:17]
	s_mov_b32 m0, s37
	s_add_i32 s38, s27, 0x8000
	global_load_lds_dwordx4 v132, s[16:17]
	s_mov_b32 m0, s38
	s_add_i32 s39, s27, 0xa000
	v_lshl_add_u32 v253, v1, 2, s15
	global_load_lds_dwordx4 v130, s[8:9]
	s_mov_b32 m0, s39
	s_mov_b32 s55, s80
	global_load_lds_dwordx4 v132, s[8:9]
	s_add_u32 s8, s18, 0x80
	s_addc_u32 s9, s19, 0
	s_add_i32 s40, s27, 0x1c000
	s_mov_b32 m0, s40
	s_add_i32 s41, s27, 0x1e000
	s_nop 0
	global_load_lds_dwordx4 v130, s[8:9]
	s_mov_b32 m0, s41
	s_nop 0
	global_load_lds_dwordx4 v132, s[8:9]
	s_add_u32 s8, s20, 0x80
	s_addc_u32 s9, s21, 0
	s_add_i32 s42, s27, 0xc000
	s_mov_b32 m0, s42
	s_add_i32 s43, s27, 0xe000
	s_cmp_eq_u32 s12, 1
	global_load_lds_dwordx4 v130, s[8:9]
	s_mov_b32 m0, s43
	s_nop 0
	global_load_lds_dwordx4 v132, s[8:9]
	s_cselect_b64 s[8:9], -1, 0
	s_add_u32 s44, s10, 0x5300780
	s_addc_u32 s45, s11, 0
	s_cmpk_lt_u32 s14, 0x100
	s_cselect_b64 s[10:11], -1, 0
	s_lshl_b32 s46, s12, 6
	s_lshl_b32 s13, s13, 5
	s_lshl_b32 s12, s12, 8
	s_or_b32 s47, s46, 16
	s_or_b32 s48, s46, 32
	s_or_b32 s49, s46, 48
	s_add_i32 s50, s46, 0x80
	s_add_i32 s51, s46, 0x90
	s_add_i32 s52, s46, 0xa0
	s_add_i32 s53, s46, 0xb0
	s_add_i32 s54, s15, s12
	s_lshl_b32 s74, s13, 1
	s_waitcnt vmcnt(16)
	v_add_f32_e32 v164, v160, v161
	v_add_f32_e32 v164, v162, v164
	v_add_f32_e32 v164, v163, v164
	v_fmamk_f32 v164, v164, 0x3a800000, v208
	v_mul_f32_e32 v165, 0x4b800000, v164
	v_cmp_gt_f32_e64 s[12:13], s95, v164
	s_nop 1
	v_cndmask_b32_e64 v164, v164, v165, s[12:13]
	v_rsq_f32_e32 v164, v164
	s_nop 0
	v_mul_f32_e32 v165, 0x45800000, v164
	v_cndmask_b32_e64 v206, v164, v165, s[12:13]
	s_branch .LBB0_355

.LBB0_453:
	v_readlane_b32 s2, v254, 39
	v_mbcnt_lo_u32_b32 v2, -1, 0
	v_mbcnt_hi_u32_b32 v2, -1, v2
	s_nop 0
	v_and_b32_e32 v3, 48, v2
	v_add_u32_e32 v1, s2, v2
	v_lshlrev_b32_e32 v4, 6, v1
	v_readfirstlane_b32 s14, v1
	s_ashr_i32 s15, s14, 6
	s_ashr_i32 s12, s14, 8
	s_and_b32 s13, s15, 3
	s_lshl_b32 s2, s12, 13
	v_lshlrev_b32_e32 v5, 2, v1
	s_cmp_lg_u32 0, -1
	v_and_b32_e32 v4, 0x3c0, v4
	v_and_b32_e32 v5, 32, v5
	s_cselect_b32 s3, 0, 0
	v_bitop3_b32 v3, v4, v5, v3 bitop3:0x36
	s_add_i32 s2, s2, s3
	v_add_u32_e32 v136, s2, v3
	s_lshl_b32 s2, s13, 12
	s_add_i32 s2, s3, s2
	s_add_i32 s2, s2, 0x10000
	v_add_u32_e32 v137, s2, v3
	v_readlane_b32 s2, v254, 25
	v_readlane_b32 s3, v254, 26
	s_andn2_b64 vcc, exec, s[2:3]
	s_cbranch_vccnz .LBB0_474
	s_waitcnt lgkmcnt(0)
	s_add_u32 s2, s10, 0x1b300000
	s_addc_u32 s3, s11, 0
	v_cmp_gt_i32_e64 s[4:5], s0, v1
	v_mov_b32_e32 v252, 0
	s_and_saveexec_b64 s[8:9], s[4:5]
	s_cbranch_execz .LBB0_456
	v_readlane_b32 s16, v254, 47
	v_readlane_b32 s17, v254, 48
	s_nop 0
	v_add_u32_e32 v4, s16, v1
	v_ashrrev_i32_e32 v5, 31, v4
	v_lshl_add_u64 v[4:5], v[4:5], 4, s[2:3]
	global_load_dwordx4 v[160:163], v[4:5], off
.LBB0_456:
	s_or_b64 exec, exec, s[8:9]
	v_bfe_i32 v5, v1, 27, 1
	v_lshlrev_b32_e32 v3, 4, v1
	v_lshrrev_b32_e32 v5, 22, v5
	v_add_u32_e32 v5, v3, v5
	v_and_b32_e32 v5, 0xfffffc00, v5
	v_sub_u32_e32 v5, v3, v5
	v_lshrrev_b32_e32 v6, 4, v5
	v_ashrrev_i32_e32 v4, 31, v1
	v_bitop3_b32 v5, v6, v5, 32 bitop3:0x6c
	v_lshrrev_b32_e32 v4, 26, v4
	v_ashrrev_i32_e32 v7, 31, v5
	v_add_u32_e32 v4, v1, v4
	v_lshrrev_b32_e32 v7, 26, v7
	v_ashrrev_i32_e32 v4, 6, v4
	v_add_u32_e32 v7, v5, v7
	v_lshlrev_b32_e32 v6, 3, v4
	v_lshrrev_b32_e32 v8, 6, v7
	v_and_b32_e32 v7, 0xc0, v7
	v_and_b32_e32 v6, 0x1ffff0, v6
	v_lshlrev_b32_e32 v4, 5, v4
	v_sub_u32_e32 v5, v5, v7
	v_add_u32_e32 v6, v8, v6
	v_and_b32_e32 v4, 32, v4
	v_ashrrev_i16_sdwa v5, v207, sext(v5) dst_sel:DWORD dst_unused:UNUSED_PAD src0_sel:DWORD src1_sel:BYTE_0
	v_bfe_i32 v5, v5, 0, 16
	v_lshl_or_b32 v4, v6, 10, v4
	v_add_u32_e32 v3, 0x2000, v3
	v_add_lshl_u32 v130, v4, v5, 1
	v_ashrrev_i32_e32 v4, 31, v3
	v_lshrrev_b32_e32 v4, 22, v4
	v_add_u32_e32 v4, v3, v4
	s_add_u32 s20, s10, 0x5300000
	v_ashrrev_i32_e32 v4, 10, v4
	s_addc_u32 s21, s11, 0
	v_mul_i32_i24_e32 v5, 0x400, v4
	s_add_u32 s22, s10, s6
	v_sub_u32_e32 v3, v3, v5
	s_addc_u32 s23, s11, s7
	v_lshrrev_b32_e32 v5, 4, v3
	s_add_u32 s6, s10, 0x9300000
	v_bitop3_b32 v3, v5, v3, 32 bitop3:0x6c
	s_mul_i32 s8, s15, 0x900
	s_addc_u32 s7, s11, 0
	v_ashrrev_i32_e32 v6, 31, v3
	s_add_i32 s24, s8, 0
	v_lshrrev_b32_e32 v6, 26, v6
	s_add_i32 s24, s24, 0x20000
	v_readlane_b32 s8, v254, 27
	v_add_u32_e32 v6, v3, v6
	v_readlane_b32 s9, v254, 28
	s_add_u32 s8, s22, s8
	v_lshlrev_b32_e32 v5, 3, v4
	v_lshrrev_b32_e32 v7, 6, v6
	v_and_b32_e32 v6, 0xc0, v6
	s_addc_u32 s9, s23, s9
	s_lshl_b32 s15, s15, 10
	v_and_b32_e32 v5, 0x1ffff0, v5
	v_lshlrev_b32_e32 v4, 5, v4
	v_sub_u32_e32 v3, v3, v6
	s_add_i32 s25, s15, 0
	v_add_u32_e32 v5, v7, v5
	v_and_b32_e32 v4, 32, v4
	v_ashrrev_i16_sdwa v3, v207, sext(v3) dst_sel:DWORD dst_unused:UNUSED_PAD src0_sel:DWORD src1_sel:BYTE_0
	s_add_i32 s26, s25, 0x10000
	v_bfe_i32 v3, v3, 0, 16
	v_lshl_or_b32 v4, v5, 10, v4
	s_mov_b64 s[16:17], s[8:9]
	s_mov_b32 m0, s26
	s_add_i32 s27, s25, 0x12000
	v_add_lshl_u32 v132, v4, v3, 1
	v_readlane_b32 s15, v254, 44
	global_load_lds_dwordx4 v130, s[16:17]
	s_mov_b32 m0, s27
	v_and_b32_e32 v253, 63, v2
	global_load_lds_dwordx4 v132, s[16:17]
	v_readlane_b32 s16, v254, 49
	v_readlane_b32 s17, v254, 50
	s_add_u32 s16, s20, s16
	s_addc_u32 s17, s21, s17
	s_mov_b64 s[18:19], s[16:17]
	s_mov_b32 m0, s25
	s_add_i32 s28, s25, 0x2000
	v_mov_b32_e32 v131, v0
	global_load_lds_dwordx4 v130, s[18:19]
	s_mov_b32 m0, s28
	v_mov_b32_e32 v133, v0
	global_load_lds_dwordx4 v132, s[18:19]
	v_readlane_b32 s18, v254, 29
	v_readlane_b32 s19, v254, 30
	s_add_u32 s18, s22, s18
	s_addc_u32 s19, s23, s19
	s_add_i32 s29, s25, 0x14000
	s_mov_b64 s[34:35], s[18:19]
	s_mov_b32 m0, s29
	s_add_i32 s30, s25, 0x16000
	v_lshl_add_u32 v206, v1, 2, s15
	global_load_lds_dwordx4 v130, s[34:35]
	s_mov_b32 m0, s30
	s_mov_b32 s49, s80
	global_load_lds_dwordx4 v132, s[34:35]
	v_readlane_b32 s34, v254, 31
	v_readlane_b32 s35, v254, 32
	s_add_u32 s40, s20, s34
	s_addc_u32 s41, s21, s35
	s_add_i32 s31, s25, 0x4000
	s_mov_b64 s[34:35], s[40:41]
	s_mov_b32 m0, s31
	s_add_i32 s33, s25, 0x6000
	s_add_u32 s8, s8, 0x80
	global_load_lds_dwordx4 v130, s[34:35]
	s_mov_b32 m0, s33
	s_addc_u32 s9, s9, 0
	global_load_lds_dwordx4 v132, s[34:35]
	s_add_i32 s34, s25, 0x18000
	s_mov_b32 m0, s34
	s_add_i32 s35, s25, 0x1a000
	s_nop 0
	global_load_lds_dwordx4 v130, s[8:9]
	s_mov_b32 m0, s35
	s_nop 0
	global_load_lds_dwordx4 v132, s[8:9]
	s_add_u32 s8, s16, 0x80
	s_addc_u32 s9, s17, 0
	s_add_i32 s36, s25, 0x8000
	s_mov_b32 m0, s36
	s_add_i32 s37, s25, 0xa000
	s_nop 0
	global_load_lds_dwordx4 v130, s[8:9]
	s_mov_b32 m0, s37
	s_nop 0
	global_load_lds_dwordx4 v132, s[8:9]
	s_add_u32 s8, s18, 0x80
	s_addc_u32 s9, s19, 0
	s_add_i32 s38, s25, 0x1c000
	s_mov_b32 m0, s38
	s_add_i32 s39, s25, 0x1e000
	s_nop 0
	global_load_lds_dwordx4 v130, s[8:9]
	s_mov_b32 m0, s39
	s_nop 0
	global_load_lds_dwordx4 v132, s[8:9]
	s_add_u32 s8, s40, 0x80
	s_addc_u32 s9, s41, 0
	s_add_i32 s40, s25, 0xc000
	s_mov_b32 m0, s40
	s_add_i32 s41, s25, 0xe000
	s_cmp_eq_u32 s12, 1
	global_load_lds_dwordx4 v130, s[8:9]
	s_mov_b32 m0, s41
	s_nop 0
	global_load_lds_dwordx4 v132, s[8:9]
	s_cselect_b64 s[8:9], -1, 0
	s_add_u32 s42, s10, 0x5300780
	s_addc_u32 s43, s11, 0
	s_cmpk_lt_u32 s14, 0x100
	s_cselect_b64 s[10:11], -1, 0
	s_lshl_b32 s44, s12, 6
	s_lshl_b32 s13, s13, 5
	s_lshl_b32 s12, s12, 8
	s_or_b32 s45, s44, 16
	s_or_b32 s46, s44, 32
	s_or_b32 s47, s44, 48
	s_add_i32 s48, s15, s12
	s_lshl_b32 s74, s13, 1
	s_waitcnt vmcnt(16)
	v_add_f32_e32 v164, v160, v161
	v_add_f32_e32 v164, v162, v164
	v_add_f32_e32 v164, v163, v164
	v_fmamk_f32 v164, v164, 0x3a800000, v208
	v_mul_f32_e32 v165, 0x4b800000, v164
	v_cmp_gt_f32_e64 s[12:13], s95, v164
	s_nop 1
	v_cndmask_b32_e64 v164, v164, v165, s[12:13]
	v_rsq_f32_e32 v164, v164
	s_nop 0
	v_mul_f32_e32 v165, 0x45800000, v164
	v_cndmask_b32_e64 v252, v164, v165, s[12:13]
	s_branch .LBB0_459
